# phase 4: chunk_pre waves run at priority 2 so the co-resident (now non-critical) scan waves no longer delay the 5-round chunk_pre blocks
# speedup vs baseline: 1.0591x; 1.0063x over previous
.LBB0_639:
	s_setprio 2
	s_sub_i32 s3, s94, 64
	s_sub_i32 s88, s2, 64
	v_writelane_b32 v242, s96, 33
	s_cmpk_gt_i32 s88, 0x7ff
	s_nop 0
	v_writelane_b32 v242, s97, 34
	s_cbranch_scc1 .LBB0_728
	v_mbcnt_lo_u32_b32 v4, -1, 0
	v_mbcnt_hi_u32_b32 v4, -1, v4
	v_and_b32_e32 v8, 64, v4
	v_xor_b32_e32 v6, 1, v4
	v_add_u32_e32 v8, 64, v8
	v_cmp_lt_i32_e32 vcc, v6, v8
	v_and_b32_e32 v2, 7, v218
	v_lshrrev_b32_e32 v0, 3, v218
	v_cndmask_b32_e32 v6, v4, v6, vcc
	s_waitcnt vmcnt(4)
	v_lshlrev_b32_e32 v94, 2, v6
	v_xor_b32_e32 v6, 2, v4
	v_cmp_lt_i32_e32 vcc, v6, v8
	v_lshlrev_b32_e32 v92, 3, v2
	v_cmp_eq_u32_e64 s[6:7], 0, v2
	v_cndmask_b32_e32 v6, v4, v6, vcc
	v_lshlrev_b32_e32 v95, 2, v6
	v_xor_b32_e32 v6, 4, v4
	v_cmp_lt_i32_e32 vcc, v6, v8
	v_or_b32_e32 v93, 0x400, v0
	s_movk_i32 s0, 0x80
	v_cndmask_b32_e32 v4, v4, v6, vcc
	v_lshlrev_b32_e32 v96, 2, v4
	v_lshlrev_b32_e32 v4, 5, v2
	v_lshlrev_b32_e32 v6, 4, v2
	v_mul_u32_u24_e32 v2, 0x140, v2
	v_lshl_or_b32 v97, v0, 8, v4
	v_mul_u32_u24_e32 v4, 0x48, v0
	v_add_lshl_u32 v100, v2, v0, 1
	v_and_b32_e32 v0, 64, v218
	v_lshl_add_u32 v99, v4, 1, v6
	v_mov_b32_e32 v2, 0x2400
	v_mov_b32_e32 v4, 0x1200
	v_cmp_eq_u32_e32 vcc, 0, v0
	v_and_b32_e32 v5, 15, v218
	v_and_b32_e32 v101, 48, v218
	v_cndmask_b32_e32 v0, v2, v4, vcc
	v_mov_b32_e32 v2, 0x3600
	v_cmp_gt_u32_e32 vcc, s0, v218
	v_mul_u32_u24_e32 v6, 0x48, v5
	v_lshrrev_b32_e32 v3, 6, v218
	v_cndmask_b32_e64 v2, v2, 0, vcc
	v_or_b32_e32 v0, v101, v0
	v_or_b32_e32 v2, v2, v101
	v_lshlrev_b32_e32 v6, 1, v6
	v_add_u32_e32 v102, v0, v6
	v_add_u32_e32 v103, v2, v6
	v_mov_b32_e32 v0, 0x8400
	v_mov_b32_e32 v2, 0x7a00
	v_cmp_eq_u32_e32 vcc, 2, v3
	v_bfe_u32 v7, v218, 4, 2
	v_lshlrev_b32_e32 v4, 3, v7
	v_cndmask_b32_e32 v0, v0, v2, vcc
	v_mov_b32_e32 v2, 0x7000
	v_cmp_eq_u32_e32 vcc, 1, v3
	v_mul_u32_u24_e32 v104, 0x50, v5
	v_or_b32_e32 v8, 16, v5
	v_cndmask_b32_e32 v2, v0, v2, vcc
	v_lshlrev_b32_e32 v0, 2, v7
	v_cmp_lt_u32_e64 s[12:13], v0, v5
	v_cmp_le_u32_e64 s[0:1], v0, v5
	v_add3_u32 v105, v2, v104, v4
	v_cndmask_b32_e64 v6, 0, 1, s[12:13]
	v_cndmask_b32_e64 v9, 0, 1, s[0:1]
	v_cndmask_b32_e32 v6, v9, v6, vcc
	v_and_b32_e32 v6, 1, v6
	v_or_b32_e32 v2, 1, v0
	v_cmp_eq_u32_e64 s[14:15], 1, v6
	v_cndmask_b32_e32 v6, v0, v2, vcc
	v_cmp_lt_u32_e64 s[52:53], v2, v5
	v_or_b32_e32 v2, 2, v0
	v_cmp_lt_u32_e64 s[36:37], v2, v5
	v_cmp_le_u32_e64 s[0:1], v2, v5
	v_cmp_gt_u32_e64 s[50:51], v5, v6
	v_cndmask_b32_e64 v6, 0, 1, s[36:37]
	v_cndmask_b32_e64 v2, 0, 1, s[0:1]
	v_cndmask_b32_e32 v2, v2, v6, vcc
	v_and_b32_e32 v2, 1, v2
	v_cmp_eq_u32_e64 s[54:55], 1, v2
	v_or_b32_e32 v2, 3, v0
	v_cmp_lt_u32_e64 s[40:41], v2, v5
	v_cmp_le_u32_e64 s[0:1], v2, v5
	v_or_b32_e32 v9, 19, v0
	v_cndmask_b32_e64 v6, 0, 1, s[40:41]
	v_cndmask_b32_e64 v2, 0, 1, s[0:1]
	v_cndmask_b32_e32 v2, v2, v6, vcc
	v_and_b32_e32 v2, 1, v2
	v_cmp_eq_u32_e64 s[56:57], 1, v2
	v_or_b32_e32 v2, 17, v0
	v_cmp_lt_u32_e64 s[58:59], v2, v8
	v_cmp_le_u32_e64 s[0:1], v2, v8
	v_or_b32_e32 v6, 18, v0
	v_cndmask_b32_e64 v10, 0, 1, s[58:59]
	v_cndmask_b32_e64 v2, 0, 1, s[0:1]
	v_cndmask_b32_e32 v2, v2, v10, vcc
	v_and_b32_e32 v2, 1, v2
	v_cmp_lt_u32_e64 s[34:35], v6, v8
	v_cmp_le_u32_e64 s[0:1], v6, v8
	v_cmp_eq_u32_e64 s[60:61], 1, v2
	v_cndmask_b32_e64 v2, 0, 1, s[34:35]
	v_cndmask_b32_e64 v6, 0, 1, s[0:1]
	v_cndmask_b32_e32 v2, v6, v2, vcc
	v_and_b32_e32 v2, 1, v2
	v_cmp_lt_u32_e64 s[38:39], v9, v8
	v_cmp_le_u32_e64 s[0:1], v9, v8
	v_cmp_eq_u32_e64 s[62:63], 1, v2
	v_cndmask_b32_e64 v2, 0, 1, s[38:39]
	v_cndmask_b32_e64 v6, 0, 1, s[0:1]
	v_cndmask_b32_e32 v2, v6, v2, vcc
	v_and_b32_e32 v2, 1, v2
	v_and_b32_e32 v1, 63, v218
	v_cmp_eq_u32_e64 s[0:1], 1, v2
	v_cmp_gt_u32_e64 s[10:11], 64, v218
	v_cmp_gt_u32_e32 vcc, 32, v1
	v_writelane_b32 v242, s0, 35
	v_lshlrev_b32_e32 v110, 1, v1
	v_lshl_or_b32 v62, v3, 7, v1
	v_writelane_b32 v242, s1, 36
	s_and_b64 s[0:1], s[10:11], vcc
	v_cmp_eq_u32_e32 vcc, 0, v1
	v_lshl_or_b32 v64, v3, 8, v1
	v_lshlrev_b32_e32 v2, 4, v3
	v_cndmask_b32_e64 v111, 0, 1.0, vcc
	v_cmp_eq_u32_e32 vcc, 1, v1
	v_lshl_or_b32 v11, v3, 5, v4
	v_lshlrev_b32_e32 v9, 1, v5
	v_cndmask_b32_e64 v113, 0, 1.0, vcc
	v_cmp_eq_u32_e32 vcc, 2, v1
	s_movk_i32 s42, 0x50
	v_or_b32_e32 v6, v2, v5
	v_cndmask_b32_e64 v114, 0, 1.0, vcc
	v_cmp_eq_u32_e32 vcc, 3, v1
	v_mul_u32_u24_e32 v6, 40, v6
	v_lshl_or_b32 v108, v8, 7, v101
	v_cndmask_b32_e64 v115, 0, 1.0, vcc
	v_cmp_eq_u32_e32 vcc, 4, v1
	v_lshl_add_u32 v109, v6, 1, v101
	v_lshlrev_b32_e32 v6, 6, v8
	v_cndmask_b32_e64 v116, 0, 1.0, vcc
	v_cmp_eq_u32_e32 vcc, 5, v1
	v_lshl_or_b32 v106, v5, 7, v101
	v_mul_u32_u24_e32 v12, 0x90, v5
	v_cndmask_b32_e64 v117, 0, 1.0, vcc
	v_cmp_eq_u32_e32 vcc, 6, v1
	v_lshlrev_b32_e32 v4, 6, v5
	v_lshlrev_b32_e32 v146, 2, v5
	v_cndmask_b32_e64 v118, 0, 1.0, vcc
	v_cmp_eq_u32_e32 vcc, 7, v1
	v_readlane_b32 s16, v242, 25
	v_readlane_b32 s22, v242, 31
	v_cndmask_b32_e64 v119, 0, 1.0, vcc
	v_cmp_eq_u32_e32 vcc, 8, v1
	v_mov_b32_e32 v61, 0
	v_readlane_b32 s18, v242, 27
	v_cndmask_b32_e64 v120, 0, 1.0, vcc
	v_cmp_eq_u32_e32 vcc, 9, v1
	v_readlane_b32 s19, v242, 28
	s_lshl_b32 s91, s22, 3
	v_cndmask_b32_e64 v121, 0, 1.0, vcc
	v_cmp_eq_u32_e32 vcc, 10, v1
	s_lshl_b32 s93, s22, 1
	v_cmp_lt_u32_e64 s[4:5], 7, v218
	v_cndmask_b32_e64 v122, 0, 1.0, vcc
	v_cmp_eq_u32_e32 vcc, 11, v1
	s_mov_b32 s49, 0
	v_cmp_lt_u32_e64 s[8:9], 63, v218
	v_cndmask_b32_e64 v123, 0, 1.0, vcc
	v_cmp_eq_u32_e32 vcc, 12, v1
	v_lshlrev_b32_e32 v98, 2, v218
	v_add_u32_e32 v107, 0x500, v105
	v_cndmask_b32_e64 v124, 0, 1.0, vcc
	v_cmp_eq_u32_e32 vcc, 13, v1
	v_cvt_pk_bf16_f32 v112, v111, s0
	v_mov_b32_e32 v63, v61
	v_cndmask_b32_e64 v125, 0, 1.0, vcc
	v_cmp_eq_u32_e32 vcc, 14, v1
	v_mov_b32_e32 v65, v61
	s_addk_i32 s91, 0xfe00
	v_cndmask_b32_e64 v126, 0, 1.0, vcc
	v_cmp_eq_u32_e32 vcc, 15, v1
	s_addk_i32 s93, 0xff80
	v_mov_b64_e32 v[76:77], s[18:19]
	v_cndmask_b32_e64 v127, 0, 1.0, vcc
	v_cmp_eq_u32_e32 vcc, 16, v1
	v_mov_b32_e32 v162, 0x260
	v_lshlrev_b32_e32 v78, 1, v2
	v_cndmask_b32_e64 v128, 0, 1.0, vcc
	v_cmp_eq_u32_e32 vcc, 17, v1
	v_lshlrev_b32_e32 v80, 1, v0
	s_mov_b64 s[72:73], 0x2000
	v_cndmask_b32_e64 v129, 0, 1.0, vcc
	v_cmp_eq_u32_e32 vcc, 18, v1
	v_add_u32_e32 v165, v11, v12
	v_lshlrev_b32_e32 v82, 1, v4
	v_cndmask_b32_e64 v130, 0, 1.0, vcc
	v_cmp_eq_u32_e32 vcc, 19, v1
	v_lshlrev_b32_e32 v84, 1, v6
	s_mov_b32 s94, 0x5040100
	v_cndmask_b32_e64 v131, 0, 1.0, vcc
	v_cmp_eq_u32_e32 vcc, 20, v1
	s_mov_b32 s95, s88
	v_readlane_b32 s17, v242, 26
	v_cndmask_b32_e64 v132, 0, 1.0, vcc
	v_cmp_eq_u32_e32 vcc, 21, v1
	v_readlane_b32 s20, v242, 29
	v_readlane_b32 s21, v242, 30
	v_cndmask_b32_e64 v133, 0, 1.0, vcc
	v_cmp_eq_u32_e32 vcc, 22, v1
	v_readlane_b32 s23, v242, 32
	s_nop 0
	v_cndmask_b32_e64 v134, 0, 1.0, vcc
	v_cmp_eq_u32_e32 vcc, 23, v1
	s_nop 1
	v_cndmask_b32_e64 v135, 0, 1.0, vcc
	v_cmp_eq_u32_e32 vcc, 24, v1
	s_nop 1
	v_cndmask_b32_e64 v136, 0, 1.0, vcc
	v_cmp_eq_u32_e32 vcc, 25, v1
	s_nop 1
	v_cndmask_b32_e64 v137, 0, 1.0, vcc
	v_cmp_eq_u32_e32 vcc, 26, v1
	s_nop 1
	v_cndmask_b32_e64 v138, 0, 1.0, vcc
	v_cmp_eq_u32_e32 vcc, 27, v1
	s_nop 1
	v_cndmask_b32_e64 v139, 0, 1.0, vcc
	v_cmp_eq_u32_e32 vcc, 28, v1
	s_nop 1
	v_cndmask_b32_e64 v140, 0, 1.0, vcc
	v_cmp_eq_u32_e32 vcc, 29, v1
	s_nop 1
	v_cndmask_b32_e64 v141, 0, 1.0, vcc
	v_cmp_eq_u32_e32 vcc, 30, v1
	s_nop 1
	v_cndmask_b32_e64 v142, 0, 1.0, vcc
	v_cmp_eq_u32_e32 vcc, 31, v1
	v_mul_u32_u24_e32 v1, 0x240, v7
	v_or_b32_e32 v3, v1, v5
	v_lshlrev_b32_e32 v144, 1, v3
	v_or_b32_e32 v3, v0, v2
	v_cndmask_b32_e64 v143, 0, 1.0, vcc
	v_or_b32_e32 v10, 1, v3
	v_mul_u32_u24_e32 v13, 40, v3
	v_cmp_eq_u32_e32 vcc, v3, v5
	v_or_b32_e32 v14, v13, v5
	v_lshl_or_b32 v148, v13, 1, v9
	v_cndmask_b32_e64 v66, 0, 1.0, vcc
	v_cmp_eq_u32_e32 vcc, v10, v5
	v_or_b32_e32 v13, 3, v3
	v_lshlrev_b32_e32 v147, 1, v14
	v_cndmask_b32_e64 v67, 0, 1.0, vcc
	v_or_b32_e32 v14, 2, v3
	v_cmp_eq_u32_e32 vcc, v13, v5
	v_mul_lo_u32 v16, v13, s42
	v_add_u32_e32 v151, v9, v16
	v_cndmask_b32_e64 v69, 0, 1.0, vcc
	v_cmp_eq_u32_e32 vcc, v14, v5
	v_or_b32_e32 v16, v1, v8
	v_mul_lo_u32 v17, v14, 40
	v_cndmask_b32_e64 v68, 0, 1.0, vcc
	v_cmp_eq_u32_e32 vcc, v3, v8
	v_or_b32_e32 v18, v17, v5
	v_mul_lo_u32 v15, v14, s42
	v_cndmask_b32_e64 v154, 0, 1.0, vcc
	v_cmp_eq_u32_e32 vcc, v10, v8
	s_lshl_b32 s42, s2, 3
	v_lshl_or_b32 v145, v1, 1, v9
	v_cndmask_b32_e64 v155, 0, 1.0, vcc
	v_cmp_eq_u32_e32 vcc, v13, v8
	v_mul_u32_u24_e32 v7, 0x50, v3
	v_lshlrev_b32_e32 v153, 1, v16
	v_cndmask_b32_e64 v71, 0, 1.0, vcc
	v_cmp_eq_u32_e32 vcc, v14, v8
	v_or_b32_e32 v8, 32, v5
	v_or_b32_e32 v5, 48, v5
	v_cndmask_b32_e64 v70, 0, 1.0, vcc
	v_cmp_eq_u32_e32 vcc, v3, v8
	v_or_b32_e32 v16, v1, v8
	v_or_b32_e32 v1, v1, v5
	v_cndmask_b32_e64 v157, 0, 1.0, vcc
	v_cmp_eq_u32_e32 vcc, v10, v8
	s_add_i32 s89, s42, 0xfffffe00
	s_lshl_b32 s42, s2, 1
	v_cndmask_b32_e64 v158, 0, 1.0, vcc
	v_cmp_eq_u32_e32 vcc, v13, v8
	v_add_u32_e32 v149, 0x50, v148
	v_lshlrev_b32_e32 v150, 1, v18
	v_cndmask_b32_e64 v73, 0, 1.0, vcc
	v_cmp_eq_u32_e32 vcc, v14, v8
	v_lshlrev_b32_e32 v8, 6, v8
	v_lshl_add_u32 v152, v17, 1, v9
	v_cndmask_b32_e64 v72, 0, 1.0, vcc
	v_cmp_eq_u32_e32 vcc, v3, v5
	v_lshlrev_b32_e32 v156, 1, v16
	v_lshlrev_b32_e32 v159, 1, v1
	v_cndmask_b32_e64 v160, 0, 1.0, vcc
	v_cmp_eq_u32_e32 vcc, v10, v5
	v_lshlrev_b32_e32 v10, 6, v5
	s_add_i32 s92, s42, 0xffffff80
	v_cndmask_b32_e64 v161, 0, 1.0, vcc
	v_cmp_eq_u32_e32 vcc, v13, v5
	v_add_u32_e32 v163, v9, v7
	v_add_u32_e32 v164, v9, v15
	v_cndmask_b32_e64 v75, 0, 1.0, vcc
	v_cmp_eq_u32_e32 vcc, v14, v5
	v_lshlrev_b32_e32 v86, 1, v8
	v_lshlrev_b32_e32 v88, 1, v10
	v_cndmask_b32_e64 v74, 0, 1.0, vcc
	s_branch .LBB0_642

.LBB0_728:
	s_setprio 0
	s_abs_i32 s0, s3
	v_cvt_f32_u32_e32 v0, s0
	v_cvt_f32_u32_e32 v1, s3
	s_sub_i32 s4, 0, s0
	s_add_i32 s1, s3, s88
	v_rcp_iflag_f32_e32 v0, v0
	v_rcp_iflag_f32_e32 v1, v1
	v_readlane_b32 s88, v242, 25
	v_readlane_b32 s96, v242, 33
	v_mul_f32_e32 v0, 0x4f7ffffe, v0
	v_cvt_u32_f32_e32 v0, v0
	v_mul_f32_e32 v1, 0x4f7ffffe, v1
	v_cvt_u32_f32_e32 v1, v1
	v_readlane_b32 s89, v242, 26
	v_readfirstlane_b32 s5, v0
	s_mul_i32 s4, s4, s5
	s_mul_hi_u32 s4, s5, s4
	s_add_i32 s5, s5, s4
	s_lshr_b32 s4, s5, 21
	s_mul_i32 s4, s4, s0
	s_sub_i32 s4, 0x800, s4
	s_sub_i32 s5, s4, s0
	s_cmp_ge_u32 s4, s0
	s_cselect_b32 s4, s5, s4
	s_sub_i32 s5, s4, s0
	s_cmp_ge_u32 s4, s0
	s_cselect_b32 s0, s5, s4
	s_sub_i32 s4, 0, s3
	s_sub_i32 s0, s1, s0
	v_readfirstlane_b32 s1, v1
	s_mul_i32 s4, s4, s1
	s_mul_hi_u32 s4, s1, s4
	s_add_i32 s1, s1, s4
	s_mul_hi_u32 s1, s0, s1
	s_mul_i32 s1, s1, s3
	s_sub_i32 s0, s0, s1
	s_sub_i32 s1, s0, s3
	s_cmp_ge_u32 s0, s3
	s_cselect_b32 s0, s1, s0
	s_sub_i32 s1, s0, s3
	s_cmp_ge_u32 s0, s3
	s_cselect_b32 s4, s1, s0
	s_cmpk_gt_i32 s4, 0x20f
	v_readlane_b32 s90, v242, 27
	v_readlane_b32 s91, v242, 28
	v_readlane_b32 s92, v242, 29
	v_readlane_b32 s93, v242, 30
	v_readlane_b32 s94, v242, 31
	v_readlane_b32 s95, v242, 32
	v_readlane_b32 s97, v242, 34
	s_barrier
	s_cbranch_scc1 .LBB0_733
	s_cmp_lg_u32 s100, 1
	s_cbranch_scc1 .LBB0_733
	v_lshrrev_b32_e32 v1, 2, v218
	v_lshrrev_b32_e32 v0, 1, v218
	v_and_b32_e32 v1, 12, v1
	s_movk_i32 s0, 0x1c0
	v_and_or_b32 v0, v0, s0, v1
	v_and_b32_e32 v1, 0x4f, v218
	v_and_b32_e32 v2, 16, v218
	v_and_b32_e32 v3, 0x5f, v218
	v_bitop3_b32 v4, v1, v218, 16 bitop3:0x72
	v_bitop3_b32 v1, v1, v2, 48 bitop3:0x36
	v_lshlrev_b32_e32 v3, 2, v3
	v_lshlrev_b32_e32 v0, 9, v0
	v_lshlrev_b32_e32 v4, 2, v4
	v_lshlrev_b32_e32 v2, 2, v1
	v_mov_b32_e32 v1, 0
	s_movk_i32 s5, 0xa0
	v_add_u32_e32 v6, v3, v0
	v_add_u32_e32 v7, v4, v0
	v_add_u32_e32 v8, v2, v0
